# W1/W3 f32->bf16 weight conversion of layers 1,3 moved from phase 0 into the idle tail of the abin GEMM phase of layers 0,2 (WGs 64-255)
# baseline (speedup 1.0000x reference)
.LBB0_6:
	v_readlane_b32 s20, v252, 0
	v_readlane_b32 s21, v252, 1
	s_add_u32 s0, s20, 0x208
	s_load_dwordx16 s[56:71], s[20:21], 0x130
	s_addc_u32 s1, s21, 0
	v_writelane_b32 v252, s0, 10
	s_load_dwordx16 s[36:51], s[20:21], 0x170
	v_lshrrev_b32_e32 v1, 20, v0
	v_writelane_b32 v252, s1, 11
	s_add_u32 s0, s20, 0x200
	s_addc_u32 s1, s21, 0
	v_writelane_b32 v252, s0, 12
	s_waitcnt lgkmcnt(0)
	s_cmp_lg_u64 s[70:71], 0
	s_cselect_b64 s[4:5], -1, 0
	v_writelane_b32 v252, s1, 13
	v_writelane_b32 v252, s4, 14
	s_load_dword s1, s[20:21], 0x2a0
	s_mul_i32 s0, s35, s34
	v_writelane_b32 v252, s5, 15
	s_add_u32 s4, s36, 0x3000000
	s_addc_u32 s5, s37, 0
	v_writelane_b32 v252, s4, 16
	s_waitcnt lgkmcnt(0)
	s_mul_i32 s90, s0, s1
	v_lshrrev_b32_e32 v0, 10, v0
	v_writelane_b32 v252, s5, 17
	s_add_u32 s4, s36, 0x2000000
	s_addc_u32 s5, s37, 0
	v_writelane_b32 v252, s4, 18
	v_or_b32_e32 v0, v0, v1
	v_mov_b32_e32 v1, 0
	v_writelane_b32 v252, s5, 19
	v_mbcnt_lo_u32_b32 v2, -1, 0
	v_readlane_b32 s4, v252, 6
	v_readlane_b32 s5, v252, 7
	s_add_u32 s0, s4, 0x200
	s_addc_u32 s1, s5, 0
	v_writelane_b32 v252, s0, 20
	v_mov_b32_e32 v197, 0x358637bd
	v_mov_b32_e32 v200, 0x3000
	v_writelane_b32 v252, s1, 21
	s_add_u32 s0, s4, 0x1000
	s_addc_u32 s1, s5, 0
	v_writelane_b32 v252, s0, 22
	v_mov_b32_e32 v201, 0x6000
	v_mov_b32_e32 v202, 0x3a27c5ac
	v_writelane_b32 v252, s1, 23
	s_add_u32 s0, s4, 0x1100
	s_addc_u32 s1, s5, 0
	v_writelane_b32 v252, s0, 24
	v_mov_b32_e32 v204, 0x260
	v_mov_b32_e32 v206, 0x3c0881c4
	v_writelane_b32 v252, s1, 25
	s_add_u32 s0, s4, 0x1200
	s_addc_u32 s1, s5, 0
	v_writelane_b32 v252, s0, 26
	v_mov_b32_e32 v207, 0xbab64f3b
	v_mbcnt_hi_u32_b32 v209, -1, v2
	v_writelane_b32 v252, s1, 27
	s_add_u32 s0, s4, 0x1300
	s_addc_u32 s1, s5, 0
	v_writelane_b32 v252, s0, 28
	s_cmp_eq_u32 s3, 15
	v_mov_b32_e32 v210, v1
	v_writelane_b32 v252, s1, 29
	s_cselect_b64 s[0:1], -1, 0
	v_writelane_b32 v252, s0, 30
	s_cmp_eq_u32 s3, 14
	v_mov_b32_e32 v211, v1
	v_writelane_b32 v252, s1, 31
	s_cselect_b64 s[0:1], -1, 0
	v_writelane_b32 v252, s0, 32
	s_cmp_eq_u32 s3, 13
	v_mov_b32_e32 v212, v1
	v_writelane_b32 v252, s1, 33
	s_cselect_b64 s[0:1], -1, 0
	v_writelane_b32 v252, s0, 34
	s_cmp_eq_u32 s3, 12
	v_mov_b32_e32 v213, v1
	v_writelane_b32 v252, s1, 35
	s_cselect_b64 s[0:1], -1, 0
	v_writelane_b32 v252, s0, 36
	s_cmp_eq_u32 s3, 11
	v_mov_b32_e32 v208, 0xfffffd80
	v_writelane_b32 v252, s1, 37
	s_cselect_b64 s[0:1], -1, 0
	v_writelane_b32 v252, s0, 38
	s_cmp_eq_u32 s3, 10
	v_mov_b32_e32 v203, 0xfffffce0
	v_writelane_b32 v252, s1, 39
	s_cselect_b64 s[0:1], -1, 0
	v_writelane_b32 v252, s0, 40
	s_cmp_eq_u32 s3, 9
	v_mov_b32_e32 v223, 0xfffffc40
	v_writelane_b32 v252, s1, 41
	s_cselect_b64 s[0:1], -1, 0
	v_writelane_b32 v252, s0, 42
	s_cmp_eq_u32 s3, 8
	v_mov_b32_e32 v229, 0xfffffb50
	v_writelane_b32 v252, s1, 43
	s_cselect_b64 s[0:1], -1, 0
	v_writelane_b32 v252, s0, 44
	s_cmp_eq_u32 s3, 7
	v_mov_b32_e32 v230, 0xfffffb00
	v_writelane_b32 v252, s1, 45
	s_cselect_b64 s[0:1], -1, 0
	v_writelane_b32 v252, s0, 46
	s_cmp_eq_u32 s3, 6
	v_mov_b32_e32 v205, 0xfffff9c0
	v_writelane_b32 v252, s1, 47
	s_cselect_b64 s[0:1], -1, 0
	v_writelane_b32 v252, s0, 48
	s_cmp_eq_u32 s3, 5
	v_mov_b32_e32 v198, 0x7f800000
	v_writelane_b32 v252, s1, 49
	s_cselect_b64 s[0:1], -1, 0
	v_writelane_b32 v252, s0, 50
	s_cmp_eq_u32 s3, 4
	v_mov_b32_e32 v199, 0x100
	v_writelane_b32 v252, s1, 51
	s_cselect_b64 s[0:1], -1, 0
	v_writelane_b32 v252, s0, 52
	s_cmp_eq_u32 s3, 3
	v_mov_b32_e32 v250, 0x41b17218
	v_writelane_b32 v252, s1, 53
	s_cselect_b64 s[0:1], -1, 0
	v_writelane_b32 v252, s0, 54
	s_cmp_eq_u32 s3, 2
	v_mov_b32_e32 v251, 0x1c00
	v_writelane_b32 v252, s1, 55
	s_cselect_b64 s[0:1], -1, 0
	v_writelane_b32 v252, s0, 56
	s_cmp_eq_u32 s3, 1
	v_mov_b32_e32 v222, 0x800
	v_writelane_b32 v252, s1, 57
	s_cselect_b64 s[0:1], -1, 0
	v_writelane_b32 v252, s0, 58
	s_cmp_eq_u32 s3, 0
	v_not_b32_e32 v224, 63
	v_writelane_b32 v252, s1, 59
	s_cselect_b64 s[0:1], -1, 0
	v_writelane_b32 v252, s0, 60
	v_not_b32_e32 v225, 31
	v_mov_b32_e32 v226, 0xffc00000
	v_writelane_b32 v252, s1, 61
	s_lshl_b32 s0, s3, 8
	s_add_u32 s0, s4, s0
	s_addc_u32 s1, s5, 0
	s_add_u32 s6, s0, 0x1400
	s_addc_u32 s7, s1, 0
	s_add_u32 s0, s0, 0x2400
	s_addc_u32 s1, s1, 0
	v_writelane_b32 v253, s0, 0
	v_writelane_b32 v252, s6, 62
	v_mov_b32_e32 v227, 0x7fc00000
	v_writelane_b32 v253, s1, 1
	s_add_u32 s0, s4, 0x3400
	s_addc_u32 s1, s5, 0
	v_writelane_b32 v253, s0, 2
	v_writelane_b32 v252, s7, 63
	v_mov_b32_e32 v228, 0x900
	v_writelane_b32 v253, s1, 3
	s_add_u32 s0, s4, 0x3500
	s_addc_u32 s1, s5, 0
	v_writelane_b32 v253, s0, 4
	s_mov_b32 s3, 0x2aaaaaab
	s_mov_b32 s96, 0x3c000
	v_writelane_b32 v253, s1, 5
	s_movk_i32 s0, 0x3ff
	v_and_or_b32 v0, v0, s0, v196
	s_load_dwordx2 s[0:1], s[20:21], 0x288
	s_load_dwordx4 s[4:7], s[20:21], 0x278
	s_movk_i32 s93, 0x1f8
	s_mov_b32 s35, 0x18000
	s_mov_b32 s97, 0x54000
	s_mov_b32 s31, 0
	s_waitcnt lgkmcnt(0)
	s_add_u32 s8, s6, 0x80000
	v_writelane_b32 v253, s4, 6
	s_addc_u32 s9, s7, 0
	s_nop 0
	v_writelane_b32 v253, s5, 7
	v_writelane_b32 v253, s6, 8
	v_writelane_b32 v253, s7, 9
	v_writelane_b32 v253, s8, 10
	s_add_u32 s4, s62, 0x100000
	s_addc_u32 s5, s63, 0
	v_writelane_b32 v253, s9, 11
	v_writelane_b32 v253, s4, 12
	s_nop 1
	v_writelane_b32 v253, s5, 13
	s_add_u32 s4, s42, 8
	v_writelane_b32 v253, s36, 14
	s_addc_u32 s5, s43, 0
	s_nop 0
	v_writelane_b32 v253, s37, 15
	v_writelane_b32 v253, s38, 16
	v_writelane_b32 v253, s39, 17
	v_writelane_b32 v253, s40, 18
	v_writelane_b32 v253, s41, 19
	v_writelane_b32 v253, s42, 20
	v_writelane_b32 v253, s43, 21
	v_writelane_b32 v253, s44, 22
	v_writelane_b32 v253, s45, 23
	v_writelane_b32 v253, s46, 24
	v_writelane_b32 v253, s47, 25
	v_writelane_b32 v253, s48, 26
	v_writelane_b32 v253, s49, 27
	v_writelane_b32 v253, s50, 28
	v_writelane_b32 v253, s51, 29
	v_writelane_b32 v253, s4, 30
	s_mov_b32 s36, 0xc000
	s_mov_b32 s39, 0x3e8293ee
	v_writelane_b32 v253, s5, 31
	s_add_u32 s4, s0, 0x2400
	v_writelane_b32 v253, s0, 32
	s_addc_u32 s5, s1, 0
	s_mov_b32 s38, 0x42000
	v_writelane_b32 v253, s1, 33
	v_writelane_b32 v253, s4, 34
	s_mov_b32 s37, 0x4ec4ec4f
	s_nop 0
	v_writelane_b32 v253, s5, 35
	s_load_dwordx8 s[4:11], s[20:21], 0x230
	s_waitcnt lgkmcnt(0)
	s_add_u32 s0, s4, 0x800
	v_writelane_b32 v253, s4, 36
	s_addc_u32 s1, s5, 0
	s_nop 0
	v_writelane_b32 v253, s5, 37
	v_writelane_b32 v253, s6, 38
	v_writelane_b32 v253, s7, 39
	v_writelane_b32 v253, s8, 40
	v_writelane_b32 v253, s9, 41
	v_writelane_b32 v253, s10, 42
	v_writelane_b32 v253, s11, 43
	s_load_dwordx16 s[4:19], s[20:21], 0x1f0
	v_writelane_b32 v253, s0, 44
	s_nop 1
	v_writelane_b32 v253, s1, 45
	s_waitcnt lgkmcnt(0)
	s_add_u32 s0, s16, 0x1000
	v_writelane_b32 v253, s4, 46
	s_addc_u32 s1, s17, 0
	s_nop 0
	v_writelane_b32 v253, s5, 47
	v_writelane_b32 v253, s6, 48
	v_writelane_b32 v253, s7, 49
	v_writelane_b32 v253, s8, 50
	v_writelane_b32 v253, s9, 51
	v_writelane_b32 v253, s10, 52
	v_writelane_b32 v253, s11, 53
	v_writelane_b32 v253, s12, 54
	v_writelane_b32 v253, s13, 55
	v_writelane_b32 v253, s14, 56
	v_writelane_b32 v253, s15, 57
	v_writelane_b32 v253, s16, 58
	v_writelane_b32 v253, s17, 59
	v_writelane_b32 v253, s18, 60
	v_writelane_b32 v253, s19, 61
	s_load_dwordx16 s[4:19], s[20:21], 0x1b0
	v_writelane_b32 v253, s0, 62
	s_nop 1
	v_writelane_b32 v253, s1, 63
	s_waitcnt lgkmcnt(0)
	s_add_u32 s0, s14, 0x200
	v_writelane_b32 v254, s4, 0
	s_addc_u32 s1, s15, 0
	s_nop 0
	v_writelane_b32 v254, s5, 1
	v_writelane_b32 v254, s6, 2
	v_writelane_b32 v254, s7, 3
	v_writelane_b32 v254, s8, 4
	v_writelane_b32 v254, s9, 5
	v_writelane_b32 v254, s10, 6
	v_writelane_b32 v254, s11, 7
	v_writelane_b32 v254, s12, 8
	v_writelane_b32 v254, s13, 9
	v_writelane_b32 v254, s14, 10
	v_writelane_b32 v254, s15, 11
	v_writelane_b32 v254, s16, 12
	v_writelane_b32 v254, s17, 13
	v_writelane_b32 v254, s18, 14
	v_writelane_b32 v254, s19, 15
	v_writelane_b32 v254, s0, 16
	s_load_dwordx4 s[4:7], s[20:21], 0x250
	s_nop 0
	v_writelane_b32 v254, s1, 17
	s_add_i32 s0, 16, 0x14000
	v_writelane_b32 v254, s0, 18
	v_readlane_b32 s0, v252, 8
	v_readlane_b32 s1, v252, 9
	s_mov_b32 s30, s0
	v_cmp_eq_u32_e64 s[0:1], 0, v0
	s_nop 1
	v_writelane_b32 v254, s0, 19
	s_nop 1
	v_writelane_b32 v254, s1, 20
	s_load_dwordx2 s[0:1], s[20:21], 0x260
	s_load_dwordx8 s[8:15], s[20:21], 0x0
	s_load_dwordx16 s[40:55], s[20:21], 0x30
	s_load_dwordx16 s[72:87], s[20:21], 0xf0
	s_waitcnt lgkmcnt(0)
	v_writelane_b32 v254, s0, 21
	s_nop 1
	v_writelane_b32 v254, s1, 22
	v_writelane_b32 v254, s4, 23
	s_nop 1
	v_writelane_b32 v254, s5, 24
	v_writelane_b32 v254, s6, 25
	v_writelane_b32 v254, s7, 26
	v_writelane_b32 v254, s40, 27
	s_nop 1
	v_writelane_b32 v254, s41, 28
	v_writelane_b32 v254, s42, 29
	v_writelane_b32 v254, s43, 30
	v_writelane_b32 v254, s44, 31
	v_writelane_b32 v254, s45, 32
	v_writelane_b32 v254, s46, 33
	v_writelane_b32 v254, s47, 34
	v_writelane_b32 v254, s48, 35
	v_writelane_b32 v254, s49, 36
	v_writelane_b32 v254, s50, 37
	v_writelane_b32 v254, s51, 38
	v_writelane_b32 v254, s52, 39
	v_writelane_b32 v254, s53, 40
	v_writelane_b32 v254, s54, 41
	v_writelane_b32 v254, s55, 42
	s_load_dwordx16 s[40:55], s[20:21], 0xb0
	s_waitcnt lgkmcnt(0)
	v_writelane_b32 v254, s40, 43
	s_nop 1
	v_writelane_b32 v254, s41, 44
	v_writelane_b32 v254, s42, 45
	v_writelane_b32 v254, s43, 46
	v_writelane_b32 v254, s44, 47
	v_writelane_b32 v254, s45, 48
	v_writelane_b32 v254, s46, 49
	v_writelane_b32 v254, s47, 50
	v_writelane_b32 v254, s48, 51
	v_writelane_b32 v254, s49, 52
	v_writelane_b32 v254, s50, 53
	v_writelane_b32 v254, s51, 54
	v_writelane_b32 v254, s52, 55
	v_writelane_b32 v254, s53, 56
	v_writelane_b32 v254, s54, 57
	v_writelane_b32 v254, s55, 58
	s_load_dwordx16 s[40:55], s[20:21], 0x70
	s_waitcnt lgkmcnt(0)
	v_writelane_b32 v254, s40, 59
	s_nop 1
	v_writelane_b32 v255, s45, 0
	v_writelane_b32 v255, s46, 1
	v_writelane_b32 v255, s47, 2
	v_writelane_b32 v255, s48, 3
	v_writelane_b32 v255, s49, 4
	v_writelane_b32 v255, s50, 5
	v_writelane_b32 v255, s51, 6
	v_writelane_b32 v255, s52, 7
	v_writelane_b32 v255, s53, 8
	v_writelane_b32 v255, s54, 9
	v_writelane_b32 v255, s55, 10
	v_writelane_b32 v255, s90, 11
	v_writelane_b32 v255, s8, 12
	v_writelane_b32 v254, s41, 60
	v_writelane_b32 v254, s42, 61
	v_writelane_b32 v255, s9, 13
	v_writelane_b32 v255, s10, 14
	v_writelane_b32 v255, s11, 15
	v_writelane_b32 v255, s12, 16
	v_writelane_b32 v255, s13, 17
	v_writelane_b32 v254, s43, 62
	v_writelane_b32 v255, s14, 18
	v_writelane_b32 v254, s44, 63
	v_writelane_b32 v255, s15, 19
	v_writelane_b32 v255, 0, 45
	v_writelane_b32 v255, 0, 44
	s_branch .LBB0_11

.LBB0_931:
	s_bitcmp1_b32 s54, 0
	s_cbranch_scc1 .Lconv_skip
	s_cmp_lt_u32 s2, 64
	s_cbranch_scc1 .Lconv_skip
	v_writelane_b32 v255, s4, 30
	v_writelane_b32 v255, s5, 31
	v_writelane_b32 v255, s6, 32
	v_writelane_b32 v255, s7, 33
	v_writelane_b32 v255, s8, 34
	v_writelane_b32 v255, s9, 35
	v_writelane_b32 v255, s10, 36
	v_writelane_b32 v255, s11, 37
	v_writelane_b32 v255, s12, 38
	v_writelane_b32 v255, s13, 39
	v_writelane_b32 v255, s14, 40
	v_writelane_b32 v255, s15, 41
	v_writelane_b32 v255, s16, 42
	v_writelane_b32 v255, s17, 43
	v_writelane_b32 v255, s18, 46
	v_writelane_b32 v255, s19, 47
	v_writelane_b32 v255, s20, 48
	v_writelane_b32 v255, s21, 49
	v_writelane_b32 v255, s22, 50
	v_writelane_b32 v255, s23, 51
	v_writelane_b32 v255, s27, 52
	v_writelane_b32 v255, s28, 53
	v_writelane_b32 v255, s29, 54
	v_writelane_b32 v255, s40, 55
	v_writelane_b32 v255, s41, 56
	v_writelane_b32 v255, s42, 57
	v_writelane_b32 v255, s2, 62
	v_writelane_b32 v255, s34, 63
	s_mov_b32 s0, 1
	s_nop 0
	v_writelane_b32 v255, s0, 44
	s_mov_b32 s43, 0xb000
	s_mov_b32 s44, 0x16000
	s_mov_b32 s45, 0x21000
	s_mov_b32 s46, 0x84000
	s_mov_b32 s47, 0x2c000
	s_mov_b32 s48, 0x37000
	s_mov_b32 s49, 0xb00
	s_mov_b32 s50, 0x4d000
	s_mov_b32 s51, 0x58000
	s_add_i32 s26, s54, 1
	s_sub_i32 s2, s2, 64
	s_sub_i32 s34, s34, 64
	s_branch .LBB0_1058
.Lconv_ret:
	v_writelane_b32 v255, 0, 44
	v_readlane_b32 s2, v255, 62
	v_readlane_b32 s34, v255, 63
	v_readlane_b32 s4, v255, 30
	v_readlane_b32 s5, v255, 31
	v_readlane_b32 s6, v255, 32
	v_readlane_b32 s7, v255, 33
	v_readlane_b32 s8, v255, 34
	v_readlane_b32 s9, v255, 35
	v_readlane_b32 s10, v255, 36
	v_readlane_b32 s11, v255, 37
	v_readlane_b32 s12, v255, 38
	v_readlane_b32 s13, v255, 39
	v_readlane_b32 s14, v255, 40
	v_readlane_b32 s15, v255, 41
	v_readlane_b32 s16, v255, 42
	v_readlane_b32 s17, v255, 43
	v_readlane_b32 s18, v255, 46
	v_readlane_b32 s19, v255, 47
	v_readlane_b32 s20, v255, 48
	v_readlane_b32 s21, v255, 49
	v_readlane_b32 s22, v255, 50
	v_readlane_b32 s23, v255, 51
	v_readlane_b32 s27, v255, 52
	v_readlane_b32 s28, v255, 53
	v_readlane_b32 s29, v255, 54
	v_readlane_b32 s40, v255, 55
	v_readlane_b32 s41, v255, 56
	v_readlane_b32 s42, v255, 57

.LBB0_1058:
	v_readlane_b32 s0, v255, 44
	s_cmp_lg_u32 s0, 0
	s_cbranch_scc1 .Lconv_go
	s_bitcmp1_b32 s26, 0
	s_cbranch_scc0 .Lconv_go
	s_mul_hi_u32 s29, s26, 0x2c0000
	s_mul_i32 s28, s26, 0x2c0000
	s_branch .LBB0_1068

.LBB0_1068:
	v_readlane_b32 s0, v255, 44
	s_cmp_lg_u32 s0, 0
	s_cbranch_scc1 .Lconv_ret
	v_mov_b32_e32 v4, v196
	s_mov_b32 s0, s2
	v_mov_b32_e32 v0, v196
	s_lshl_b32 s0, s0, 1
	v_readfirstlane_b32 s1, v0
	s_ashr_i32 s1, s1, 8
	v_mov_b32_e32 v0, v196
	s_add_i32 s1, s1, s0
	s_nop 0
	v_readfirstlane_b32 s0, v0
	s_ashr_i32 s0, s0, 8
	s_sub_i32 s22, s1, s0
	s_cmpk_gt_i32 s22, 0x2bf
	s_cbranch_scc1 .LBB0_1057
	v_readlane_b32 s4, v253, 14
	s_lshl_b64 s[0:1], s[28:29], 1
	v_readlane_b32 s18, v253, 28
	v_readlane_b32 s5, v253, 15
	v_readlane_b32 s6, v253, 16
	v_readlane_b32 s7, v253, 17
	v_readlane_b32 s8, v253, 18
	v_readlane_b32 s9, v253, 19
	v_readlane_b32 s10, v253, 20
	v_readlane_b32 s11, v253, 21
	v_readlane_b32 s12, v253, 22
	v_readlane_b32 s13, v253, 23
	v_readlane_b32 s14, v253, 24
	v_readlane_b32 s15, v253, 25
	v_readlane_b32 s16, v253, 26
	v_readlane_b32 s17, v253, 27
	v_readlane_b32 s19, v253, 29
	s_add_u32 s0, s18, s0
	s_addc_u32 s1, s19, s1
	s_mul_i32 s20, s26, 0xb00000
	v_readlane_b32 s4, v254, 59
	v_mov_b32_e32 v0, v196
	s_mul_hi_u32 s21, s26, 0xb00000
	v_readlane_b32 s5, v254, 60
	s_add_u32 s20, s4, s20
	s_addc_u32 s21, s5, s21
	v_readfirstlane_b32 s23, v0
	s_ashr_i32 s23, s23, 8
	s_add_i32 s23, s23, s22
	s_min_i32 s23, s23, 0x2bf
	s_mul_hi_i32 s27, s23, 0x2e8ba2e9
	s_lshr_b32 s28, s27, 31
	s_ashr_i32 s27, s27, 3
	s_add_i32 s27, s27, s28
	s_mul_i32 s28, s27, 44
	s_sub_i32 s23, s23, s28
	s_lshl_b32 s28, s27, 6
	v_bfe_u32 v6, v4, 6, 2
	s_ashr_i32 s29, s28, 31
	v_lshl_or_b32 v2, s23, 6, v6
	s_lshl_b64 s[28:29], s[28:29], 2
	s_add_u32 s28, s20, s28
	v_lshlrev_b32_e32 v0, 2, v4
	s_waitcnt vmcnt(15)
	v_or_b32_e32 v10, 4, v2
	s_waitcnt vmcnt(13)
	v_or_b32_e32 v12, 8, v2
	s_waitcnt vmcnt(12)
	v_or_b32_e32 v14, 12, v2
	s_waitcnt vmcnt(0)
	v_or_b32_e32 v16, 16, v2
	v_or_b32_e32 v22, 20, v2
	v_or_b32_e32 v24, 24, v2
	v_or_b32_e32 v26, 28, v2
	s_addc_u32 s29, s21, s29
	v_and_b32_e32 v0, 0xfc, v0
	v_ashrrev_i32_e32 v3, 31, v2
	v_ashrrev_i32_e32 v11, 31, v10
	v_ashrrev_i32_e32 v13, 31, v12
	v_ashrrev_i32_e32 v15, 31, v14
	v_ashrrev_i32_e32 v17, 31, v16
	s_waitcnt lgkmcnt(4)
	v_ashrrev_i32_e32 v23, 31, v22
	v_ashrrev_i32_e32 v25, 31, v24
	v_ashrrev_i32_e32 v27, 31, v26
	v_lshl_add_u64 v[20:21], s[28:29], 0, v[0:1]
	v_lshlrev_b64 v[8:9], 12, v[2:3]
	v_lshlrev_b64 v[10:11], 12, v[10:11]
	v_lshlrev_b64 v[12:13], 12, v[12:13]
	v_lshlrev_b64 v[14:15], 12, v[14:15]
	v_lshlrev_b64 v[16:17], 12, v[16:17]
	v_lshlrev_b64 v[22:23], 12, v[22:23]
	v_lshlrev_b64 v[24:25], 12, v[24:25]
	v_lshlrev_b64 v[26:27], 12, v[26:27]
	v_lshl_add_u64 v[8:9], v[20:21], 0, v[8:9]
	v_lshl_add_u64 v[10:11], v[20:21], 0, v[10:11]
	v_lshl_add_u64 v[12:13], v[20:21], 0, v[12:13]
	v_lshl_add_u64 v[14:15], v[20:21], 0, v[14:15]
	v_lshl_add_u64 v[16:17], v[20:21], 0, v[16:17]
	v_lshl_add_u64 v[22:23], v[20:21], 0, v[22:23]
	v_lshl_add_u64 v[24:25], v[20:21], 0, v[24:25]
	v_lshl_add_u64 v[26:27], v[20:21], 0, v[26:27]
	global_load_dword v8, v[8:9], off nt
	s_nop 0
	global_load_dword v9, v[10:11], off nt
	s_nop 0
	global_load_dword v11, v[12:13], off nt
	s_nop 0
	global_load_dword v13, v[14:15], off nt
	s_nop 0
	global_load_dword v14, v[16:17], off nt
	global_load_dword v15, v[22:23], off nt
	s_nop 0
	global_load_dword v16, v[24:25], off nt
	global_load_dword v17, v[26:27], off nt
	v_or_b32_e32 v22, 32, v2
	v_or_b32_e32 v24, 36, v2
	v_or_b32_e32 v26, 40, v2
	v_ashrrev_i32_e32 v23, 31, v22
	v_ashrrev_i32_e32 v25, 31, v24
	v_ashrrev_i32_e32 v27, 31, v26
	v_or_b32_e32 v28, 44, v2
	v_or_b32_e32 v30, 48, v2
	s_waitcnt lgkmcnt(0)
	v_or_b32_e32 v32, 52, v2
	v_or_b32_e32 v34, 56, v2
	v_or_b32_e32 v2, 60, v2
	v_lshlrev_b64 v[22:23], 12, v[22:23]
	v_lshlrev_b64 v[24:25], 12, v[24:25]
	v_lshlrev_b64 v[26:27], 12, v[26:27]
	v_ashrrev_i32_e32 v29, 31, v28
	v_ashrrev_i32_e32 v31, 31, v30
	v_ashrrev_i32_e32 v33, 31, v32
	v_ashrrev_i32_e32 v35, 31, v34
	v_ashrrev_i32_e32 v3, 31, v2
	v_lshl_add_u64 v[22:23], v[20:21], 0, v[22:23]
	v_lshl_add_u64 v[24:25], v[20:21], 0, v[24:25]
	v_lshl_add_u64 v[26:27], v[20:21], 0, v[26:27]
	v_lshlrev_b64 v[28:29], 12, v[28:29]
	v_lshlrev_b64 v[30:31], 12, v[30:31]
	v_lshlrev_b64 v[32:33], 12, v[32:33]
	v_lshlrev_b64 v[34:35], 12, v[34:35]
	v_lshlrev_b64 v[2:3], 12, v[2:3]
	v_lshl_add_u64 v[28:29], v[20:21], 0, v[28:29]
	v_lshl_add_u64 v[30:31], v[20:21], 0, v[30:31]
	v_lshl_add_u64 v[32:33], v[20:21], 0, v[32:33]
	v_lshl_add_u64 v[34:35], v[20:21], 0, v[34:35]
	v_lshl_add_u64 v[2:3], v[20:21], 0, v[2:3]
	global_load_dword v19, v[22:23], off nt
	global_load_dword v20, v[24:25], off nt
	global_load_dword v21, v[26:27], off nt
	s_nop 0
	global_load_dword v22, v[28:29], off nt
	global_load_dword v23, v[30:31], off nt
	global_load_dword v24, v[32:33], off nt
	global_load_dword v25, v[34:35], off nt
	global_load_dword v26, v[2:3], off nt
	v_bfe_u32 v7, v4, 3, 5
	v_lshlrev_b32_e32 v4, 3, v4
	v_and_b32_e32 v10, 56, v4
	v_mul_u32_u24_e32 v12, 0x41, v10
	v_lshlrev_b32_e32 v12, 2, v12
	v_lshlrev_b32_e32 v27, 2, v7
	v_lshlrev_b32_e32 v4, 1, v10
	v_mov_b32_e32 v5, v1
	v_add3_u32 v12, s33, v12, v27
	v_mul_u32_u24_e32 v27, 0x104, v6
	v_lshl_add_u64 v[2:3], s[20:21], 0, v[0:1]
	v_lshl_add_u64 v[4:5], s[0:1], 0, v[4:5]
	v_or_b32_e32 v10, 32, v7
	v_add3_u32 v0, s33, v27, v0
	v_readlane_b32 s6, v254, 61
	v_readlane_b32 s7, v254, 62
	v_readlane_b32 s8, v254, 63
	v_readlane_b32 s9, v255, 0
	v_readlane_b32 s10, v255, 1
	v_readlane_b32 s11, v255, 2
	v_readlane_b32 s12, v255, 3
	v_readlane_b32 s13, v255, 4
	v_readlane_b32 s14, v255, 5
	v_readlane_b32 s15, v255, 6
	v_readlane_b32 s16, v255, 7
	v_readlane_b32 s17, v255, 8
	v_readlane_b32 s18, v255, 9
	v_readlane_b32 s19, v255, 10
	s_branch .LBB0_1071
